# adds: merge final store and attention output store widened the same way (permlane32_swap pairs, dwordx4 stores)
# speedup vs baseline: 1.0736x; 1.0059x over previous
.LBB0_63:
	v_lshl_add_u64 v[174:175], v[118:119], 0, s[6:7]
	v_add_co_u32_e32 v178, vcc, s33, v174
	v_lshl_add_u64 v[176:177], v[122:123], 0, s[6:7]
	s_nop 0
	v_addc_co_u32_e32 v179, vcc, 0, v175, vcc
	v_add_co_u32_e32 v180, vcc, s33, v176
	s_waitcnt vmcnt(7)
	ds_write_b128 v140, v[68:71]
	v_addc_co_u32_e32 v181, vcc, 0, v177, vcc
	v_add_co_u32_e32 v182, vcc, s78, v174
	s_waitcnt vmcnt(6)
	ds_write_b128 v140, v[72:75] offset:18432
	v_addc_co_u32_e32 v183, vcc, 0, v175, vcc
	v_add_co_u32_e32 v184, vcc, s78, v176
	s_waitcnt vmcnt(5)
	ds_write_b128 v140, v[76:79] offset:4608
	v_addc_co_u32_e32 v185, vcc, 0, v177, vcc
	v_add_co_u32_e32 v186, vcc, s79, v174
	s_waitcnt vmcnt(4)
	ds_write_b128 v140, v[80:83] offset:23040
	v_addc_co_u32_e32 v187, vcc, 0, v175, vcc
	v_add_co_u32_e32 v188, vcc, s79, v176
	s_waitcnt vmcnt(3)
	ds_write_b128 v140, v[84:87] offset:9216
	v_addc_co_u32_e32 v189, vcc, 0, v177, vcc
	s_waitcnt vmcnt(2)
	ds_write_b128 v140, v[88:91] offset:27648
	s_waitcnt vmcnt(1)
	ds_write_b128 v140, v[92:95] offset:13824
	s_waitcnt vmcnt(0)
	ds_write_b128 v140, v[96:99] offset:32256
	s_waitcnt lgkmcnt(0)
	s_barrier
	global_load_dwordx4 v[92:95], v[174:175], off offset:128
	global_load_dwordx4 v[96:99], v[176:177], off offset:128
	global_load_dwordx4 v[84:87], v[178:179], off offset:128
	global_load_dwordx4 v[88:91], v[180:181], off offset:128
	global_load_dwordx4 v[72:75], v[182:183], off offset:128
	global_load_dwordx4 v[80:83], v[184:185], off offset:128
	global_load_dwordx4 v[68:71], v[186:187], off offset:128
	global_load_dwordx4 v[76:79], v[188:189], off offset:128
	ds_read_b128 v[8:11], v2 offset:23040
	ds_read_b128 v[4:7], v142 offset:4608
	ds_read_b128 v[12:15], v142
	ds_read_b128 v[194:197], v142 offset:32
	s_waitcnt lgkmcnt(1)
	v_mfma_f32_32x32x16_bf16 v[36:51], v[8:11], v[12:15], 0
	ds_read_b128 v[16:19], v2 offset:18432
	ds_read_b128 v[216:219], v2 offset:18464
	s_min_u32 s9, s5, 14
	s_lshl_b32 s42, s9, 7
	s_add_u32 s6, s6, 0x200
	s_addc_u32 s7, s7, 0
	s_add_i32 s5, s5, 4
	s_waitcnt lgkmcnt(1)
	v_mfma_f32_32x32x16_bf16 v[52:67], v[16:19], v[12:15], 0
	ds_read_b128 v[224:227], v2 offset:23072
	ds_read_b128 v[220:223], v142 offset:4640
	s_cmpk_eq_i32 s6, 0x800
	v_mfma_f32_32x32x16_bf16 v[20:35], v[16:19], v[4:7], 0
	v_mfma_f32_32x32x16_bf16 v[4:19], v[8:11], v[4:7], 0
	s_waitcnt lgkmcnt(2)
	v_mfma_f32_32x32x16_bf16 v[52:67], v[216:219], v[194:197], v[52:67]
	s_waitcnt lgkmcnt(1)
	v_mfma_f32_32x32x16_bf16 v[36:51], v[224:227], v[194:197], v[36:51]
	ds_read_b128 v[194:197], v142 offset:64
	s_waitcnt lgkmcnt(1)
	v_mfma_f32_32x32x16_bf16 v[20:35], v[216:219], v[220:223], v[20:35]
	ds_read_b128 v[216:219], v142 offset:4672
	v_mfma_f32_32x32x16_bf16 v[4:19], v[224:227], v[220:223], v[4:19]
	ds_read_b128 v[220:223], v2 offset:18496
	ds_read_b128 v[224:227], v2 offset:23104
	s_waitcnt lgkmcnt(1)
	v_mfma_f32_32x32x16_bf16 v[52:67], v[220:223], v[194:197], v[52:67]
	s_waitcnt lgkmcnt(0)
	v_mfma_f32_32x32x16_bf16 v[36:51], v[224:227], v[194:197], v[36:51]
	ds_read_b128 v[194:197], v142 offset:96
	v_mfma_f32_32x32x16_bf16 v[20:35], v[220:223], v[216:219], v[20:35]
	ds_read_b128 v[220:223], v2 offset:18528
	v_mfma_f32_32x32x16_bf16 v[4:19], v[224:227], v[216:219], v[4:19]
	ds_read_b128 v[224:227], v2 offset:23136
	ds_read_b128 v[216:219], v142 offset:4704
	s_waitcnt lgkmcnt(2)
	v_mfma_f32_32x32x16_bf16 v[52:67], v[220:223], v[194:197], v[52:67]
	s_waitcnt vmcnt(7)
	ds_write_b128 v140, v[92:95] offset:36864
	s_waitcnt vmcnt(6)
	ds_write_b128 v140, v[96:99] offset:55296
	s_waitcnt lgkmcnt(3)
	v_mfma_f32_32x32x16_bf16 v[36:51], v[224:227], v[194:197], v[36:51]
	s_waitcnt vmcnt(5)
	ds_write_b128 v140, v[84:87] offset:41472
	s_waitcnt vmcnt(4)
	ds_write_b128 v140, v[88:91] offset:59904
	s_waitcnt lgkmcnt(4)
	v_mfma_f32_32x32x16_bf16 v[20:35], v[220:223], v[216:219], v[20:35]
	s_waitcnt vmcnt(3)
	ds_write_b128 v140, v[72:75] offset:46080
	s_waitcnt vmcnt(2)
	ds_write_b128 v140, v[80:83] offset:64512
	v_mfma_f32_32x32x16_bf16 v[4:19], v[224:227], v[216:219], v[4:19]
	s_waitcnt vmcnt(1)
	ds_write_b128 v140, v[68:71] offset:50688
	s_waitcnt vmcnt(0)
	ds_write_b128 v117, v[76:79] offset:32256
	s_waitcnt lgkmcnt(0)
	s_barrier
	global_load_dwordx4 v[68:71], v[174:175], off offset:256
	global_load_dwordx4 v[72:75], v[176:177], off offset:256
	global_load_dwordx4 v[76:79], v[178:179], off offset:256
	global_load_dwordx4 v[80:83], v[180:181], off offset:256
	global_load_dwordx4 v[84:87], v[182:183], off offset:256
	global_load_dwordx4 v[88:91], v[184:185], off offset:256
	global_load_dwordx4 v[92:95], v[186:187], off offset:256
	global_load_dwordx4 v[96:99], v[188:189], off offset:256
	ds_read_b128 v[216:219], v2 offset:59904
	ds_read_b128 v[194:197], v142 offset:41472
	s_waitcnt lgkmcnt(0)
	v_mfma_f32_32x32x16_bf16 v[4:19], v[216:219], v[194:197], v[4:19]
	ds_read_b128 v[220:223], v142 offset:36864
	ds_read_b128 v[224:227], v142 offset:36896
	s_waitcnt lgkmcnt(1)
	v_mfma_f32_32x32x16_bf16 v[36:51], v[216:219], v[220:223], v[36:51]
	ds_read_b128 v[228:231], v2 offset:55296
	ds_read_b128 v[232:235], v2 offset:55328
	s_waitcnt lgkmcnt(1)
	v_mfma_f32_32x32x16_bf16 v[52:67], v[228:231], v[220:223], v[52:67]
	ds_read_b128 v[216:219], v2 offset:59936
	ds_read_b128 v[220:223], v2 offset:55360
	v_mfma_f32_32x32x16_bf16 v[20:35], v[228:231], v[194:197], v[20:35]
	ds_read_b128 v[194:197], v142 offset:41504
	s_waitcnt lgkmcnt(3)
	v_mfma_f32_32x32x16_bf16 v[52:67], v[232:235], v[224:227], v[52:67]
	s_waitcnt lgkmcnt(2)
	v_mfma_f32_32x32x16_bf16 v[36:51], v[216:219], v[224:227], v[36:51]
	ds_read_b128 v[224:227], v2 offset:59968
	s_waitcnt lgkmcnt(1)
	v_mfma_f32_32x32x16_bf16 v[20:35], v[232:235], v[194:197], v[20:35]
	v_mfma_f32_32x32x16_bf16 v[4:19], v[216:219], v[194:197], v[4:19]
	ds_read_b128 v[194:197], v142 offset:36928
	ds_read_b128 v[216:219], v142 offset:41536
	s_waitcnt lgkmcnt(1)
	v_mfma_f32_32x32x16_bf16 v[52:67], v[220:223], v[194:197], v[52:67]
	v_mfma_f32_32x32x16_bf16 v[36:51], v[224:227], v[194:197], v[36:51]
	ds_read_b128 v[194:197], v142 offset:36960
	s_waitcnt lgkmcnt(1)
	v_mfma_f32_32x32x16_bf16 v[20:35], v[220:223], v[216:219], v[20:35]
	ds_read_b128 v[220:223], v2 offset:55392
	v_mfma_f32_32x32x16_bf16 v[4:19], v[224:227], v[216:219], v[4:19]
	ds_read_b128 v[224:227], v2 offset:60000
	ds_read_b128 v[216:219], v142 offset:41568
	s_waitcnt lgkmcnt(2)
	v_mfma_f32_32x32x16_bf16 v[52:67], v[220:223], v[194:197], v[52:67]
	s_waitcnt vmcnt(7)
	ds_write_b128 v140, v[68:71]
	s_waitcnt vmcnt(6)
	ds_write_b128 v140, v[72:75] offset:18432
	s_waitcnt lgkmcnt(3)
	v_mfma_f32_32x32x16_bf16 v[36:51], v[224:227], v[194:197], v[36:51]
	s_waitcnt vmcnt(5)
	ds_write_b128 v140, v[76:79] offset:4608
	s_waitcnt vmcnt(4)
	ds_write_b128 v140, v[80:83] offset:23040
	s_waitcnt lgkmcnt(4)
	v_mfma_f32_32x32x16_bf16 v[20:35], v[220:223], v[216:219], v[20:35]
	s_waitcnt vmcnt(3)
	ds_write_b128 v140, v[84:87] offset:9216
	s_waitcnt vmcnt(2)
	ds_write_b128 v140, v[88:91] offset:27648
	v_mfma_f32_32x32x16_bf16 v[4:19], v[224:227], v[216:219], v[4:19]
	s_waitcnt vmcnt(1)
	ds_write_b128 v140, v[92:95] offset:13824
	s_waitcnt vmcnt(0)
	ds_write_b128 v140, v[96:99] offset:32256
	s_waitcnt lgkmcnt(0)
	s_barrier
	global_load_dwordx4 v[68:71], v[174:175], off offset:384
	global_load_dwordx4 v[72:75], v[176:177], off offset:384
	global_load_dwordx4 v[76:79], v[178:179], off offset:384
	global_load_dwordx4 v[80:83], v[180:181], off offset:384
	global_load_dwordx4 v[84:87], v[182:183], off offset:384
	global_load_dwordx4 v[88:91], v[184:185], off offset:384
	global_load_dwordx4 v[92:95], v[186:187], off offset:384
	global_load_dwordx4 v[96:99], v[188:189], off offset:384
	ds_read_b128 v[178:181], v2 offset:23040
	ds_read_b128 v[174:177], v142 offset:4608
	s_waitcnt lgkmcnt(0)
	v_mfma_f32_32x32x16_bf16 v[4:19], v[178:181], v[174:177], v[4:19]
	ds_read_b128 v[182:185], v142
	ds_read_b128 v[186:189], v142 offset:32
	s_waitcnt lgkmcnt(1)
	v_mfma_f32_32x32x16_bf16 v[36:51], v[178:181], v[182:185], v[36:51]
	ds_read_b128 v[194:197], v2 offset:18432
	ds_read_b128 v[216:219], v2 offset:18464
	s_waitcnt lgkmcnt(1)
	v_mfma_f32_32x32x16_bf16 v[52:67], v[194:197], v[182:185], v[52:67]
	ds_read_b128 v[178:181], v2 offset:23072
	ds_read_b128 v[182:185], v2 offset:18496
	v_mfma_f32_32x32x16_bf16 v[20:35], v[194:197], v[174:177], v[20:35]
	ds_read_b128 v[174:177], v142 offset:4640
	s_waitcnt lgkmcnt(3)
	v_mfma_f32_32x32x16_bf16 v[52:67], v[216:219], v[186:189], v[52:67]
	s_waitcnt lgkmcnt(2)
	v_mfma_f32_32x32x16_bf16 v[36:51], v[178:181], v[186:189], v[36:51]
	ds_read_b128 v[186:189], v2 offset:23104
	s_waitcnt lgkmcnt(1)
	v_mfma_f32_32x32x16_bf16 v[20:35], v[216:219], v[174:177], v[20:35]
	v_mfma_f32_32x32x16_bf16 v[4:19], v[178:181], v[174:177], v[4:19]
	ds_read_b128 v[174:177], v142 offset:64
	ds_read_b128 v[178:181], v142 offset:4672
	s_waitcnt lgkmcnt(1)
	v_mfma_f32_32x32x16_bf16 v[52:67], v[182:185], v[174:177], v[52:67]
	v_mfma_f32_32x32x16_bf16 v[36:51], v[186:189], v[174:177], v[36:51]
	ds_read_b128 v[174:177], v142 offset:96
	s_waitcnt lgkmcnt(1)
	v_mfma_f32_32x32x16_bf16 v[20:35], v[182:185], v[178:181], v[20:35]
	ds_read_b128 v[182:185], v2 offset:18528
	v_mfma_f32_32x32x16_bf16 v[4:19], v[186:189], v[178:181], v[4:19]
	ds_read_b128 v[186:189], v2 offset:23136
	ds_read_b128 v[178:181], v142 offset:4704
	s_waitcnt lgkmcnt(2)
	v_mfma_f32_32x32x16_bf16 v[52:67], v[182:185], v[174:177], v[52:67]
	s_waitcnt vmcnt(7)
	ds_write_b128 v140, v[68:71] offset:36864
	s_waitcnt vmcnt(6)
	ds_write_b128 v140, v[72:75] offset:55296
	s_waitcnt lgkmcnt(3)
	v_mfma_f32_32x32x16_bf16 v[36:51], v[186:189], v[174:177], v[36:51]
	s_waitcnt vmcnt(5)
	ds_write_b128 v140, v[76:79] offset:41472
	s_waitcnt vmcnt(4)
	ds_write_b128 v140, v[80:83] offset:59904
	s_waitcnt lgkmcnt(4)
	v_mfma_f32_32x32x16_bf16 v[20:35], v[182:185], v[178:181], v[20:35]
	s_waitcnt vmcnt(3)
	ds_write_b128 v140, v[84:87] offset:46080
	s_waitcnt vmcnt(2)
	ds_write_b128 v140, v[88:91] offset:64512
	v_mfma_f32_32x32x16_bf16 v[4:19], v[186:189], v[178:181], v[4:19]
	s_waitcnt vmcnt(1)
	ds_write_b128 v140, v[92:95] offset:50688
	s_waitcnt vmcnt(0)
	ds_write_b128 v117, v[96:99] offset:32256
	s_waitcnt lgkmcnt(0)
	s_barrier
	ds_read_b128 v[178:181], v2 offset:59904
	ds_read_b128 v[174:177], v142 offset:41472
	s_waitcnt lgkmcnt(0)
	v_mfma_f32_32x32x16_bf16 v[4:19], v[178:181], v[174:177], v[4:19]
	ds_read_b128 v[182:185], v142 offset:36864
	ds_read_b128 v[186:189], v142 offset:36896
	v_lshl_add_u64 v[92:93], v[118:119], 0, s[42:43]
	v_add_co_u32_e32 v76, vcc, s33, v92
	v_lshl_add_u64 v[96:97], v[122:123], 0, s[42:43]
	s_nop 0
	v_addc_co_u32_e32 v77, vcc, 0, v93, vcc
	s_waitcnt lgkmcnt(1)
	v_mfma_f32_32x32x16_bf16 v[36:51], v[178:181], v[182:185], v[36:51]
	ds_read_b128 v[194:197], v2 offset:55296
	ds_read_b128 v[216:219], v2 offset:55328
	v_add_co_u32_e32 v80, vcc, s33, v96
	global_load_dwordx4 v[68:71], v[92:93], off offset:128
	s_nop 0
	v_addc_co_u32_e32 v81, vcc, 0, v97, vcc
	s_waitcnt lgkmcnt(1)
	v_mfma_f32_32x32x16_bf16 v[52:67], v[194:197], v[182:185], v[52:67]
	ds_read_b128 v[178:181], v2 offset:59936
	ds_read_b128 v[182:185], v2 offset:55360
	v_add_co_u32_e32 v84, vcc, s78, v92
	global_load_dwordx4 v[72:75], v[96:97], off offset:128
	s_nop 0
	v_addc_co_u32_e32 v85, vcc, 0, v93, vcc
	v_mfma_f32_32x32x16_bf16 v[20:35], v[194:197], v[174:177], v[20:35]
	ds_read_b128 v[174:177], v142 offset:41504
	v_add_co_u32_e32 v88, vcc, s78, v96
	global_load_dwordx4 v[76:79], v[76:77], off offset:128
	s_nop 0
	v_addc_co_u32_e32 v89, vcc, 0, v97, vcc
	v_add_co_u32_e32 v92, vcc, s79, v92
	s_waitcnt lgkmcnt(3)
	v_mfma_f32_32x32x16_bf16 v[52:67], v[216:219], v[186:189], v[52:67]
	v_addc_co_u32_e32 v93, vcc, 0, v93, vcc
	v_add_co_u32_e32 v96, vcc, s79, v96
	global_load_dwordx4 v[80:83], v[80:81], off offset:128
	s_nop 0
	v_addc_co_u32_e32 v97, vcc, 0, v97, vcc
	s_waitcnt lgkmcnt(2)
	v_mfma_f32_32x32x16_bf16 v[36:51], v[178:181], v[186:189], v[36:51]
	ds_read_b128 v[186:189], v2 offset:59968
	global_load_dwordx4 v[84:87], v[84:85], off offset:128
	s_nop 0
	global_load_dwordx4 v[88:91], v[88:89], off offset:128
	s_nop 0
	global_load_dwordx4 v[92:95], v[92:93], off offset:128
	s_waitcnt lgkmcnt(1)
	v_mfma_f32_32x32x16_bf16 v[20:35], v[216:219], v[174:177], v[20:35]
	global_load_dwordx4 v[96:99], v[96:97], off offset:128
	v_mfma_f32_32x32x16_bf16 v[4:19], v[178:181], v[174:177], v[4:19]
	ds_read_b128 v[174:177], v142 offset:36928
	ds_read_b128 v[178:181], v142 offset:41536
	s_waitcnt lgkmcnt(1)
	v_mfma_f32_32x32x16_bf16 v[52:67], v[182:185], v[174:177], v[52:67]
	v_mfma_f32_32x32x16_bf16 v[36:51], v[186:189], v[174:177], v[36:51]
	ds_read_b128 v[174:177], v142 offset:36960
	s_waitcnt lgkmcnt(1)
	v_mfma_f32_32x32x16_bf16 v[20:35], v[182:185], v[178:181], v[20:35]
	ds_read_b128 v[182:185], v2 offset:55392
	v_mfma_f32_32x32x16_bf16 v[4:19], v[186:189], v[178:181], v[4:19]
	ds_read_b128 v[186:189], v2 offset:60000
	ds_read_b128 v[178:181], v142 offset:41568
	s_waitcnt lgkmcnt(2)
	v_mfma_f32_32x32x16_bf16 v[52:67], v[182:185], v[174:177], v[52:67]
	s_waitcnt lgkmcnt(1)
	v_mfma_f32_32x32x16_bf16 v[36:51], v[186:189], v[174:177], v[36:51]
	v_mov_b32_e32 v174, v141
	v_add_u32_e32 v141, 0x400, v141
	v_ashrrev_i32_e32 v175, 31, v174
	v_lshl_add_u64 v[174:175], v[174:175], 1, s[12:13]
	global_load_dwordx2 v[176:177], v[174:175], off
	s_waitcnt lgkmcnt(0)
	v_mfma_f32_32x32x16_bf16 v[20:35], v[182:185], v[178:181], v[20:35]
	v_mfma_f32_32x32x16_bf16 v[4:19], v[186:189], v[178:181], v[4:19]
	s_waitcnt vmcnt(0)
	v_lshlrev_b32_e32 v178, 16, v176
	v_and_b32_e32 v179, 0xffff0000, v176
	v_fma_f32 v170, v52, v178, v170
	v_fma_f32 v171, v53, v179, v171
	v_lshlrev_b32_e32 v52, 16, v177
	v_and_b32_e32 v53, 0xffff0000, v177
	v_pk_fma_f32 v[172:173], v[54:55], v[52:53], v[172:173]
	global_load_dwordx2 v[52:53], v[174:175], off offset:16
	s_waitcnt vmcnt(0)
	v_lshlrev_b32_e32 v54, 16, v52
	v_and_b32_e32 v55, 0xffff0000, v52
	v_lshlrev_b32_e32 v52, 16, v53
	v_and_b32_e32 v53, 0xffff0000, v53
	v_pk_fma_f32 v[168:169], v[58:59], v[52:53], v[168:169]
	global_load_dwordx2 v[52:53], v[174:175], off offset:32
	v_pk_fma_f32 v[166:167], v[56:57], v[54:55], v[166:167]
	s_waitcnt vmcnt(0)
	v_lshlrev_b32_e32 v54, 16, v52
	v_and_b32_e32 v55, 0xffff0000, v52
	v_lshlrev_b32_e32 v52, 16, v53
	v_and_b32_e32 v53, 0xffff0000, v53
	v_pk_fma_f32 v[164:165], v[62:63], v[52:53], v[164:165]
	global_load_dwordx2 v[52:53], v[174:175], off offset:48
	v_pk_fma_f32 v[162:163], v[60:61], v[54:55], v[162:163]
	s_waitcnt vmcnt(0)
	v_lshlrev_b32_e32 v54, 16, v52
	v_and_b32_e32 v55, 0xffff0000, v52
	v_lshlrev_b32_e32 v52, 16, v53
	v_and_b32_e32 v53, 0xffff0000, v53
	v_pk_fma_f32 v[158:159], v[66:67], v[52:53], v[158:159]
	global_load_dwordx2 v[52:53], v[174:175], off offset:64
	v_pk_fma_f32 v[160:161], v[64:65], v[54:55], v[160:161]
	s_waitcnt vmcnt(0)
	v_lshlrev_b32_e32 v54, 16, v52
	v_and_b32_e32 v55, 0xffff0000, v52
	v_pk_fma_f32 v[154:155], v[36:37], v[54:55], v[154:155]
	v_lshlrev_b32_e32 v36, 16, v53
	v_and_b32_e32 v37, 0xffff0000, v53
	v_pk_fma_f32 v[156:157], v[38:39], v[36:37], v[156:157]
	global_load_dwordx2 v[36:37], v[174:175], off offset:80
	s_waitcnt vmcnt(0)
	v_lshlrev_b32_e32 v38, 16, v36
	v_and_b32_e32 v39, 0xffff0000, v36
	v_lshlrev_b32_e32 v36, 16, v37
	v_and_b32_e32 v37, 0xffff0000, v37
	v_pk_fma_f32 v[152:153], v[42:43], v[36:37], v[152:153]
	global_load_dwordx2 v[36:37], v[174:175], off offset:96
	v_pk_fma_f32 v[150:151], v[40:41], v[38:39], v[150:151]
	s_waitcnt vmcnt(0)
	v_lshlrev_b32_e32 v38, 16, v36
	v_and_b32_e32 v39, 0xffff0000, v36
	v_lshlrev_b32_e32 v36, 16, v37
	v_and_b32_e32 v37, 0xffff0000, v37
	v_pk_fma_f32 v[148:149], v[46:47], v[36:37], v[148:149]
	global_load_dwordx2 v[36:37], v[174:175], off offset:112
	v_pk_fma_f32 v[146:147], v[44:45], v[38:39], v[146:147]
	s_waitcnt vmcnt(0)
	v_lshlrev_b32_e32 v38, 16, v36
	v_and_b32_e32 v39, 0xffff0000, v36
	v_lshlrev_b32_e32 v36, 16, v37
	v_and_b32_e32 v37, 0xffff0000, v37
	v_pk_fma_f32 v[138:139], v[50:51], v[36:37], v[138:139]
	v_add_co_u32_e32 v36, vcc, s72, v174
	v_pk_fma_f32 v[144:145], v[48:49], v[38:39], v[144:145]
	s_nop 0
	v_addc_co_u32_e32 v37, vcc, 0, v175, vcc
	global_load_dwordx2 v[38:39], v[36:37], off
	s_waitcnt vmcnt(0)
	v_lshlrev_b32_e32 v40, 16, v38
	v_and_b32_e32 v41, 0xffff0000, v38
	v_pk_fma_f32 v[134:135], v[20:21], v[40:41], v[134:135]
	v_lshlrev_b32_e32 v20, 16, v39
	v_and_b32_e32 v21, 0xffff0000, v39
	v_pk_fma_f32 v[136:137], v[22:23], v[20:21], v[136:137]
	global_load_dwordx2 v[20:21], v[36:37], off offset:16
	s_waitcnt vmcnt(0)
	v_lshlrev_b32_e32 v22, 16, v20
	v_and_b32_e32 v23, 0xffff0000, v20
	v_lshlrev_b32_e32 v20, 16, v21
	v_and_b32_e32 v21, 0xffff0000, v21
	v_pk_fma_f32 v[132:133], v[26:27], v[20:21], v[132:133]
	global_load_dwordx2 v[20:21], v[36:37], off offset:32
	v_pk_fma_f32 v[130:131], v[24:25], v[22:23], v[130:131]
	s_waitcnt vmcnt(0)
	v_lshlrev_b32_e32 v22, 16, v20
	v_and_b32_e32 v23, 0xffff0000, v20
	v_lshlrev_b32_e32 v20, 16, v21
	v_and_b32_e32 v21, 0xffff0000, v21
	v_pk_fma_f32 v[128:129], v[30:31], v[20:21], v[128:129]
	global_load_dwordx2 v[20:21], v[36:37], off offset:48
	v_pk_fma_f32 v[126:127], v[28:29], v[22:23], v[126:127]
	s_waitcnt vmcnt(0)
	v_lshlrev_b32_e32 v22, 16, v20
	v_and_b32_e32 v23, 0xffff0000, v20
	v_lshlrev_b32_e32 v20, 16, v21
	v_and_b32_e32 v21, 0xffff0000, v21
	v_pk_fma_f32 v[120:121], v[34:35], v[20:21], v[120:121]
	global_load_dwordx2 v[20:21], v[36:37], off offset:64
	v_pk_fma_f32 v[124:125], v[32:33], v[22:23], v[124:125]
	s_waitcnt vmcnt(0)
	v_lshlrev_b32_e32 v22, 16, v20
	v_and_b32_e32 v23, 0xffff0000, v20
	v_pk_fma_f32 v[112:113], v[4:5], v[22:23], v[112:113]
	v_lshlrev_b32_e32 v4, 16, v21
	v_and_b32_e32 v5, 0xffff0000, v21
	v_pk_fma_f32 v[114:115], v[6:7], v[4:5], v[114:115]
	global_load_dwordx2 v[4:5], v[36:37], off offset:80
	s_waitcnt vmcnt(0)
	v_lshlrev_b32_e32 v6, 16, v4
	v_and_b32_e32 v7, 0xffff0000, v4
	v_lshlrev_b32_e32 v4, 16, v5
	v_and_b32_e32 v5, 0xffff0000, v5
	v_pk_fma_f32 v[110:111], v[10:11], v[4:5], v[110:111]
	global_load_dwordx2 v[4:5], v[36:37], off offset:96
	v_pk_fma_f32 v[108:109], v[8:9], v[6:7], v[108:109]
	s_waitcnt vmcnt(0)
	v_lshlrev_b32_e32 v6, 16, v4
	v_and_b32_e32 v7, 0xffff0000, v4
	v_lshlrev_b32_e32 v4, 16, v5
	v_and_b32_e32 v5, 0xffff0000, v5
	v_pk_fma_f32 v[106:107], v[14:15], v[4:5], v[106:107]
	global_load_dwordx2 v[4:5], v[36:37], off offset:112
	v_pk_fma_f32 v[104:105], v[12:13], v[6:7], v[104:105]
	s_waitcnt vmcnt(0)
	v_lshlrev_b32_e32 v6, 16, v4
	v_and_b32_e32 v7, 0xffff0000, v4
	v_lshlrev_b32_e32 v4, 16, v5
	v_and_b32_e32 v5, 0xffff0000, v5
	v_pk_fma_f32 v[102:103], v[16:17], v[6:7], v[102:103]
	v_pk_fma_f32 v[100:101], v[18:19], v[4:5], v[100:101]
	s_cbranch_scc0 .LBB0_63
	v_ashrrev_i32_e32 v117, 31, v116
	v_readlane_b32 s12, v252, 62
	s_ashr_i32 s5, s4, 31
	v_lshlrev_b64 v[4:5], 11, v[116:117]
	v_readlane_b32 s14, v253, 0
	v_readlane_b32 s15, v253, 1
	s_lshl_b64 s[4:5], s[4:5], 1
	v_lshlrev_b32_e32 v2, 1, v213
	v_lshl_add_u64 v[4:5], s[14:15], 0, v[4:5]
	v_lshl_add_u64 v[4:5], v[4:5], 0, s[4:5]
	v_lshl_add_u64 v[4:5], v[4:5], 0, v[2:3]
	v_lshlrev_b32_e32 v6, 2, v214
	v_mov_b32_e32 v7, v3
	v_lshl_add_u64 v[4:5], v[4:5], 0, v[6:7]
	v_cvt_pk_bf16_f32 v8, v170, v171
	v_cvt_pk_bf16_f32 v9, v172, v173
	v_cvt_pk_bf16_f32 v10, v166, v167
	v_cvt_pk_bf16_f32 v11, v168, v169
	v_cvt_pk_bf16_f32 v12, v162, v163
	v_cvt_pk_bf16_f32 v13, v164, v165
	v_cvt_pk_bf16_f32 v14, v160, v161
	v_cvt_pk_bf16_f32 v15, v158, v159
	s_nop 1
	v_permlane32_swap_b32_e32 v8, v10
	v_permlane32_swap_b32_e32 v9, v11
	v_permlane32_swap_b32_e32 v12, v14
	v_permlane32_swap_b32_e32 v13, v15
	global_store_dwordx4 v[4:5], v[8:11], off
	global_store_dwordx4 v[4:5], v[12:15], off offset:32
	v_cvt_pk_bf16_f32 v16, v154, v155
	v_cvt_pk_bf16_f32 v17, v156, v157
	v_cvt_pk_bf16_f32 v18, v150, v151
	v_cvt_pk_bf16_f32 v19, v152, v153
	v_cvt_pk_bf16_f32 v20, v146, v147
	v_cvt_pk_bf16_f32 v21, v148, v149
	v_cvt_pk_bf16_f32 v22, v144, v145
	v_cvt_pk_bf16_f32 v23, v138, v139
	s_nop 1
	v_permlane32_swap_b32_e32 v16, v18
	v_permlane32_swap_b32_e32 v17, v19
	v_permlane32_swap_b32_e32 v20, v22
	v_permlane32_swap_b32_e32 v21, v23
	global_store_dwordx4 v[4:5], v[16:19], off offset:64
	global_store_dwordx4 v[4:5], v[20:23], off offset:96
	v_or_b32_e32 v4, 32, v116
	v_ashrrev_i32_e32 v5, 31, v4
	v_lshlrev_b64 v[4:5], 11, v[4:5]
	v_lshl_add_u64 v[4:5], s[14:15], 0, v[4:5]
	v_lshl_add_u64 v[4:5], v[4:5], 0, s[4:5]
	v_lshl_add_u64 v[4:5], v[4:5], 0, v[2:3]
	v_lshl_add_u64 v[4:5], v[4:5], 0, v[6:7]
	v_cvt_pk_bf16_f32 v24, v134, v135
	v_cvt_pk_bf16_f32 v25, v136, v137
	v_cvt_pk_bf16_f32 v26, v130, v131
	v_cvt_pk_bf16_f32 v27, v132, v133
	v_cvt_pk_bf16_f32 v28, v126, v127
	v_cvt_pk_bf16_f32 v29, v128, v129
	v_cvt_pk_bf16_f32 v30, v124, v125
	v_cvt_pk_bf16_f32 v31, v120, v121
	s_nop 1
	v_permlane32_swap_b32_e32 v24, v26
	v_permlane32_swap_b32_e32 v25, v27
	v_permlane32_swap_b32_e32 v28, v30
	v_permlane32_swap_b32_e32 v29, v31
	global_store_dwordx4 v[4:5], v[24:27], off
	global_store_dwordx4 v[4:5], v[28:31], off offset:32
	v_cvt_pk_bf16_f32 v32, v112, v113
	v_cvt_pk_bf16_f32 v33, v114, v115
	v_cvt_pk_bf16_f32 v34, v108, v109
	v_cvt_pk_bf16_f32 v35, v110, v111
	v_cvt_pk_bf16_f32 v36, v104, v105
	v_cvt_pk_bf16_f32 v37, v106, v107
	v_cvt_pk_bf16_f32 v38, v102, v103
	v_cvt_pk_bf16_f32 v39, v100, v101
	s_nop 1
	v_permlane32_swap_b32_e32 v32, v34
	v_permlane32_swap_b32_e32 v33, v35
	v_permlane32_swap_b32_e32 v36, v38
	v_permlane32_swap_b32_e32 v37, v39
	global_store_dwordx4 v[4:5], v[32:35], off offset:64
	global_store_dwordx4 v[4:5], v[36:39], off offset:96
	s_load_dword s4, s[62:63], 0x0
	v_readlane_b32 s13, v252, 63
	s_waitcnt lgkmcnt(0)
	s_add_i32 s8, s4, s8
	s_cmpk_gt_i32 s8, 0x1ff
	s_cbranch_scc0 .LBB0_62

.LBB0_73:
	v_readlane_b32 s0, v254, 49
	s_add_i32 s0, s0, s34
	s_lshl_b32 s0, s0, 11
	v_readlane_b32 s4, v252, 62
	v_readlane_b32 s5, v252, 63
	s_add_u32 s2, s4, s0
	s_addc_u32 s3, s5, 0
	s_lshl_b32 s0, s83, 8
	s_ashr_i32 s1, s0, 31
	s_lshl_b64 s[0:1], s[0:1], 1
	s_add_u32 s2, s2, s0
	s_addc_u32 s3, s3, s1
	v_div_scale_f32 v4, s[0:1], v2, v2, 1.0
	v_rcp_f32_e32 v5, v4
	s_lshl_b32 s0, s27, 7
	s_add_u32 s0, s2, s0
	s_addc_u32 s1, s3, 0
	v_fma_f32 v6, -v4, v5, 1.0
	v_fmac_f32_e32 v5, v6, v5
	v_div_scale_f32 v6, vcc, 1.0, v2, 1.0
	v_mul_f32_e32 v7, v6, v5
	v_fma_f32 v8, -v4, v7, v6
	v_fmac_f32_e32 v7, v8, v5
	v_fma_f32 v4, -v4, v7, v6
	v_div_fmas_f32 v4, v4, v5, v7
	v_div_fixup_f32 v2, v4, v2, 1.0
	v_lshlrev_b64 v[4:5], 11, v[174:175]
	v_lshl_add_u64 v[4:5], s[0:1], 0, v[4:5]
	v_mov_b32_e32 v177, v3
	v_lshl_add_u64 v[4:5], v[176:177], 2, v[4:5]
	v_pk_mul_f32 v[18:19], v[2:3], v[18:19] op_sel_hi:[0,1]
	v_pk_mul_f32 v[20:21], v[2:3], v[20:21] op_sel_hi:[0,1]
	v_pk_mul_f32 v[22:23], v[2:3], v[22:23] op_sel_hi:[0,1]
	v_pk_mul_f32 v[24:25], v[2:3], v[24:25] op_sel_hi:[0,1]
	v_pk_mul_f32 v[26:27], v[2:3], v[26:27] op_sel_hi:[0,1]
	v_pk_mul_f32 v[28:29], v[2:3], v[28:29] op_sel_hi:[0,1]
	v_pk_mul_f32 v[30:31], v[2:3], v[30:31] op_sel_hi:[0,1]
	v_pk_mul_f32 v[32:33], v[2:3], v[32:33] op_sel_hi:[0,1]
	v_cvt_pk_bf16_f32 v18, v18, v19
	v_cvt_pk_bf16_f32 v19, v20, v21
	v_cvt_pk_bf16_f32 v20, v22, v23
	v_cvt_pk_bf16_f32 v21, v24, v25
	v_cvt_pk_bf16_f32 v22, v26, v27
	v_cvt_pk_bf16_f32 v23, v28, v29
	v_cvt_pk_bf16_f32 v24, v30, v31
	v_cvt_pk_bf16_f32 v25, v32, v33
	s_nop 1
	v_permlane32_swap_b32_e32 v18, v20
	v_permlane32_swap_b32_e32 v19, v21
	v_permlane32_swap_b32_e32 v22, v24
	v_permlane32_swap_b32_e32 v23, v25
	global_store_dwordx4 v[4:5], v[18:21], off
	global_store_dwordx4 v[4:5], v[22:25], off offset:32
	v_pk_mul_f32 v[34:35], v[2:3], v[34:35] op_sel_hi:[0,1]
	v_pk_mul_f32 v[36:37], v[2:3], v[36:37] op_sel_hi:[0,1]
	v_pk_mul_f32 v[38:39], v[2:3], v[38:39] op_sel_hi:[0,1]
	v_pk_mul_f32 v[40:41], v[2:3], v[40:41] op_sel_hi:[0,1]
	v_pk_mul_f32 v[42:43], v[2:3], v[42:43] op_sel_hi:[0,1]
	v_pk_mul_f32 v[44:45], v[2:3], v[44:45] op_sel_hi:[0,1]
	v_pk_mul_f32 v[46:47], v[2:3], v[46:47] op_sel_hi:[0,1]
	v_pk_mul_f32 v[48:49], v[2:3], v[48:49] op_sel_hi:[0,1]
	v_cvt_pk_bf16_f32 v34, v34, v35
	v_cvt_pk_bf16_f32 v35, v36, v37
	v_cvt_pk_bf16_f32 v36, v38, v39
	v_cvt_pk_bf16_f32 v37, v40, v41
	v_cvt_pk_bf16_f32 v38, v42, v43
	v_cvt_pk_bf16_f32 v39, v44, v45
	v_cvt_pk_bf16_f32 v40, v46, v47
	v_cvt_pk_bf16_f32 v41, v48, v49
	s_nop 1
	v_permlane32_swap_b32_e32 v34, v36
	v_permlane32_swap_b32_e32 v35, v37
	v_permlane32_swap_b32_e32 v38, v40
	v_permlane32_swap_b32_e32 v39, v41
	global_store_dwordx4 v[4:5], v[34:37], off offset:64
	global_store_dwordx4 v[4:5], v[38:41], off offset:96
	s_mov_b64 s[66:67], s[38:39]
	s_mov_b64 s[0:1], 0
	s_mov_b32 s83, 0xfffffc0
	s_mov_b64 s[64:65], s[36:37]
	s_movk_i32 s36, 0x1fff
	v_readlane_b32 s6, v253, 0
	v_readlane_b32 s7, v253, 1
